# attention half 1: first V fragment (PV#1 operand) and V-slot scalar math prefetched behind QK MFMA #4
# speedup vs baseline: 1.0030x; 1.0030x over previous
; #define LAS __attribute__((address_space(3)))
; template <bool FIRST>
; __device__ __forceinline__ void partialSM(f32x16& p0, f32x16& p1, f32x16& negm, float& dl, float& alpha) {
;     float pmax = p0[0];
; #pragma unroll
;     for (int r = 1; r < 16; ++r) pmax = fmaxf(pmax, p0[r]);
; #pragma unroll
;     for (int r = 0; r < 16; ++r) pmax = fmaxf(pmax, p1[r]);
;     { auto rr = __builtin_amdgcn_permlane32_swap(__float_as_uint(pmax), __float_as_uint(pmax), false, false);
;       pmax = fmaxf(__uint_as_float(rr[0]), __uint_as_float(rr[1])); }
;     if (FIRST) {
;         dl = 0.f; alpha = 1.f; const float d0_ = pmax - SH;
; #pragma unroll
;         for (int r = 0; r < 16; ++r) { p0[r] -= d0_; p1[r] -= d0_; negm[r] -= d0_; }
;     } else {
;         const bool keep = __all(pmax <= SH + THRL);
;         dl = keep ? 0.f : fmaxf(pmax - SH, 0.f); alpha = __builtin_amdgcn_exp2f(-dl);
;     }
; #pragma unroll
;     for (int r = 0; r < 16; ++r) p0[r] = __builtin_amdgcn_exp2f(p0[r]);
; }
; __device__ __forceinline__ void finishSM(f32x16& p0, f32x16& p1, v8i& pa) {
; #pragma unroll
;     for (int r = 0; r < 16; ++r) p1[r] = __builtin_amdgcn_exp2f(p1[r]);
; #pragma unroll
;     for (int w = 0; w < 4; ++w) { pa[w] = (int)pk4_fp8(p0[4 * w], p0[4 * w + 1], p0[4 * w + 2], p0[4 * w + 3]); pa[4 + w] = (int)pk4_fp8(p1[4 * w], p1[4 * w + 1], p1[4 * w + 2], p1[4 * w + 3]); }
; }
; __device__ __forceinline__ v8i ld32(const LAS char* a0, const LAS char* a1) { const v4i x = *(const LAS v4i*)a0, y = *(const LAS v4i*)a1; return (v8i){x[0], x[1], x[2], x[3], y[0], y[1], y[2], y[3]}; }
; __device__ __forceinline__ void qkt(f32x16& p0, f32x16& p1, const LAS char* Ks, int ka0, int ka1, const v8i* qf, const f32x16& negm) {
; #pragma unroll
;     for (int st = 0; st < 3; ++st) {
;         const v8i k0 = ld32(Ks + ka0 + 64 * st, Ks + ka1 + 64 * st), k1 = ld32(Ks + ka0 + 64 * st + 32 * 192, Ks + ka1 + 64 * st + 32 * 192);
;         if (st == 0) { p0 = MFMA8QK(k0, qf[st], negm); p1 = MFMA8QK(k1, qf[st], negm); }
;         else { p0 = MFMA8QK(k0, qf[st], p0); p1 = MFMA8QK(k1, qf[st], p1); } }
; }
; __device__ __forceinline__ void pv_d0(f32x16* o, const LAS char* Vs, int va0, int va1, v8i pa) {
; #pragma unroll
;     for (int d0 = 0; d0 < 4; ++d0) { const v8i vf = ld32(Vs + va0 + 2048 * d0, Vs + va1 + 2048 * d0); o[d0] = MFMA8(pa, vf, o[d0]); }
.LBB0_589:
	s_bitcmp1_b32 s15, 0
	s_cselect_b32 s0, 0x6000, 0
	s_add_i32 s0, s0, 0
	v_add_u32_e32 v0, s0, v244
	v_add_u32_e32 v210, s0, v245
	v_add_u32_e32 v211, 0xf000, v0
	v_add_u32_e32 v212, 0xf000, v210
	ds_read_b128 v[2:5], v0 offset:61504
	ds_read_b128 v[6:9], v210 offset:61504
	v_exp_f32_e32 v14, v116
	v_exp_f32_e32 v15, v117
	v_exp_f32_e32 v12, v114
	v_exp_f32_e32 v13, v115
	s_waitcnt lgkmcnt(4)
	v_mfma_scale_f32_32x32x64_f8f6f4 v[144:159], v[202:209], v[184:191], v[96:111], v234, v233 op_sel_hi:[0,0,0]
	ds_read_b128 v[202:205], v211 offset:6208
	ds_read_b128 v[206:209], v212 offset:6208
	v_exp_f32_e32 v114, v118
	v_exp_f32_e32 v115, v119
	v_exp_f32_e32 v119, v120
	v_exp_f32_e32 v120, v121
	v_cvt_pk_fp8_f32 v117, v14, v15
	v_exp_f32_e32 v10, v112
	v_exp_f32_e32 v11, v113
	s_waitcnt lgkmcnt(4)
	v_mfma_scale_f32_32x32x64_f8f6f4 v[128:143], v[194:201], v[184:191], v[96:111], v234, v233 op_sel_hi:[0,0,0]
	ds_read_b128 v[194:197], v0 offset:61568
	ds_read_b128 v[198:201], v210 offset:61568
	v_exp_f32_e32 v121, v122
	v_exp_f32_e32 v122, v123
	v_exp_f32_e32 v123, v124
	v_exp_f32_e32 v124, v125
	v_cvt_pk_fp8_f32 v117, v114, v115 op_sel:[0,0,1]
	v_cvt_pk_fp8_f32 v118, v119, v120
	v_exp_f32_e32 v125, v126
	s_waitcnt lgkmcnt(4)
	v_mfma_scale_f32_32x32x64_f8f6f4 v[144:159], v[2:9], v[176:183], v[144:159], v234, v233 op_sel_hi:[0,0,0]
	ds_read_b128 v[2:5], v211 offset:6272
	ds_read_b128 v[6:9], v212 offset:6272
	v_exp_f32_e32 v126, v127
	v_cvt_pk_fp8_f32 v112, v228, v229
	v_cvt_pk_fp8_f32 v116, v10, v11
	v_cvt_pk_fp8_f32 v113, v226, v227
	v_cvt_pk_fp8_f32 v114, v222, v223
	v_cvt_pk_fp8_f32 v115, v166, v167
	s_waitcnt lgkmcnt(4)
	v_mfma_scale_f32_32x32x64_f8f6f4 v[128:143], v[202:209], v[176:183], v[128:143], v234, v233 op_sel_hi:[0,0,0]
	s_add_i32 s66, s21, -2
	s_ashr_i32 s38, s66, 1
	s_mul_hi_i32 s0, s38, 0x55555556
	s_lshr_b32 s1, s0, 31
	s_add_i32 s0, s0, s1
	s_mul_i32 s0, s0, 3
	s_sub_i32 s0, s38, s0
	s_lshl_b32 s0, s0, 14
	s_add_i32 s0, s0, 0
	v_add_u32_e32 v0, s0, v241
	v_add_u32_e32 v14, s0, v240
	ds_read_b128 v[208:211], v0
	ds_read_b128 v[212:215], v14
	v_cvt_pk_fp8_f32 v119, v123, v124
	v_cvt_pk_fp8_f32 v112, v220, v221 op_sel:[0,0,1]
	v_cvt_pk_fp8_f32 v116, v12, v13 op_sel:[0,0,1]
	v_cvt_pk_fp8_f32 v113, v224, v225 op_sel:[0,0,1]
	v_cvt_pk_fp8_f32 v114, v162, v163 op_sel:[0,0,1]
	v_cvt_pk_fp8_f32 v118, v121, v122 op_sel:[0,0,1]
	s_waitcnt lgkmcnt(4)
	v_mfma_scale_f32_32x32x64_f8f6f4 v[144:159], v[194:201], v[168:175], v[144:159], v234, v233 op_sel_hi:[0,0,0]
	v_cvt_pk_fp8_f32 v115, v164, v165 op_sel:[0,0,1]
	v_cvt_pk_fp8_f32 v119, v125, v126 op_sel:[0,0,1]
	v_mov_b32_e32 v161, v160
	v_mov_b32_e32 v162, v160
	v_mov_b32_e32 v163, v160
	s_waitcnt lgkmcnt(2)
	v_mfma_scale_f32_32x32x64_f8f6f4 v[128:143], v[2:9], v[168:175], v[128:143], v234, v233 op_sel_hi:[0,0,0]
	v_mov_b32_e32 v164, v160
	v_mov_b32_e32 v165, v160
	v_mov_b32_e32 v166, v160
	v_mov_b32_e32 v167, v160
	ds_read_b128 v[200:203], v0 offset:2048
	ds_read_b128 v[204:207], v14 offset:2048
	ds_read_b128 v[192:195], v0 offset:4096
	ds_read_b128 v[196:199], v14 offset:4096
	ds_read_b128 v[2:5], v0 offset:6144
	ds_read_b128 v[6:9], v14 offset:6144
	v_mov_b32_e32 v125, 0x19000
	v_lshl_add_u32 v126, v216, 4, v125
	v_lshl_add_u32 v127, v216, 2, v125
	ds_read_b128 v[120:123], v126
	ds_read_b32 v124, v127 offset:8192
	v_max_f32_e32 v0, v144, v145
	v_max3_f32 v0, v0, v146, v147
	v_max3_f32 v0, v0, v148, v149
	v_max3_f32 v0, v0, v150, v151
	v_max3_f32 v0, v0, v152, v153
	v_max3_f32 v0, v0, v154, v155
	v_max3_f32 v0, v0, v156, v157
	v_max3_f32 v0, v0, v158, v159
	s_waitcnt lgkmcnt(8)
	v_mfma_scale_f32_32x32x64_f8f6f4 v[64:79], v[112:119], v[208:215], v[64:79], v234, v234 op_sel_hi:[0,0,0]
	v_exp_f32_e32 v14, v144
	v_exp_f32_e32 v15, v145
	v_exp_f32_e32 v10, v148
	v_exp_f32_e32 v11, v149
	v_max3_f32 v0, v0, v128, v129
	v_max3_f32 v0, v0, v130, v131
	v_max3_f32 v0, v0, v132, v133
	v_max3_f32 v0, v0, v134, v135
	s_waitcnt lgkmcnt(6)
	v_mfma_scale_f32_32x32x64_f8f6f4 v[48:63], v[112:119], v[200:207], v[48:63], v234, v234 op_sel_hi:[0,0,0]
	v_exp_f32_e32 v12, v150
	v_exp_f32_e32 v13, v151
	v_max3_f32 v0, v0, v136, v137
	v_max3_f32 v0, v0, v138, v139
	v_max3_f32 v0, v0, v140, v141
	v_max3_f32 v0, v0, v142, v143
	s_waitcnt lgkmcnt(4)
	v_mfma_scale_f32_32x32x64_f8f6f4 v[32:47], v[112:119], v[192:199], v[32:47], v234, v234 op_sel_hi:[0,0,0]
	v_exp_f32_e32 v192, v146
	v_exp_f32_e32 v193, v147
	v_mov_b32_e32 v125, v0
	s_nop 1
	v_permlane32_swap_b32_e32 v0, v125
	s_waitcnt lgkmcnt(2)
	v_mfma_scale_f32_32x32x64_f8f6f4 v[16:31], v[112:119], v[2:9], v[16:31], v234, v234 op_sel_hi:[0,0,0]
	v_exp_f32_e32 v6, v152
	v_exp_f32_e32 v7, v153
	v_exp_f32_e32 v8, v154
	v_exp_f32_e32 v9, v155
	v_mfma_scale_f32_32x32x64_f8f6f4 v[80:95], v[112:119], v[160:167], v[80:95], v234, v234 op_sel_hi:[0,0,0]
	v_exp_f32_e32 v2, v156
	v_exp_f32_e32 v3, v157
	v_exp_f32_e32 v4, v158
	v_exp_f32_e32 v5, v159
	s_waitcnt vmcnt(0) lgkmcnt(0)
	s_barrier
	v_max_f32_e32 v0, v0, v125
	s_add_i32 s42, s38, 2
	v_cmp_ge_f32_e64 s[0:1], s67, v0
	s_cmp_ge_i32 s42, s14
	s_cbranch_scc1 .Lattn_noissue
	s_bitcmp1_b32 s21, 1
	s_cselect_b32 s44, 0x6000, 0
	v_add_u32_e32 v126, s44, v244
	v_add_u32_e32 v127, s44, v245
	ds_read_b128 v[208:211], v126 offset:49152
	ds_read_b128 v[212:215], v127 offset:49152
	s_ashr_i32 s43, s42, 31
	s_mul_i32 s38, s42, 0x18000
	s_mul_hi_i32 s39, s42, 0x18000
	s_add_u32 s38, s24, s38
	s_addc_u32 s39, s25, s39
	s_lshl_b64 s[40:41], s[42:43], 14
	s_add_u32 s40, s52, s40
	s_addc_u32 s41, s53, s41
	s_mul_hi_i32 s43, s42, 0x55555556
	s_lshr_b32 s67, s43, 31
	s_add_i32 s43, s43, s67
	s_mul_i32 s43, s43, 3
	s_sub_i32 s42, s42, s43
	s_lshl_b32 s67, s42, 14
	s_bitcmp1_b32 s66, 1
	s_mov_b32 s42, 0xa000
	s_cselect_b32 s66, 0x10000, s42
	s_and_b64 vcc, exec, s[6:7]
	s_cbranch_vccnz .Lattn_iss_hi
	s_add_i32 m0, s67, s28
	s_nop 0
	global_load_lds_dwordx4 v120, s[40:41]
	s_add_i32 m0, s2, s66
	s_nop 0
	global_load_lds_dwordx4 v121, s[38:39]
	s_add_i32 m0, s27, s66
	s_nop 0
	global_load_lds_dwordx4 v122, s[38:39]
	s_add_i32 m0, s67, s31
	s_nop 0
	global_load_lds_dwordx4 v123, s[40:41]
	s_add_i32 m0, s33, s66
	s_nop 0
	global_load_lds_dwordx4 v124, s[38:39]
	s_branch .Lattn_iss_done
